# C1 + GEMM prologue de-serialised: all seven prologue stages issued before the first counted wait (vmcnt 8 then 6)
# speedup vs baseline: 1.0016x; 1.0009x over previous
; #define PG8_STAGE(bufoff, gbase, voff) do { _Pragma("unroll") for (int _i = 0; _i < 2; ++_i) \
;         __builtin_amdgcn_global_load_lds((const unsigned*)((const char*)(gbase) + (voff)[_i]), (PG8_LAS unsigned*)(lds + (bufoff) + ldsw + _i * 8192), 16, 0, 0); } while (0)
; #define PG8_WAIT_V(n) asm volatile("s_waitcnt vmcnt(" #n ")" ::: "memory")
; #define PG8_BAR __builtin_amdgcn_s_barrier()
; template <class Epi, class Sched, bool ALIGN_EPI = false, bool SP2 = false, bool ABLK = false, bool BBLK = false>
; __device__ __forceinline__ void gemm_phase(PG8_LAS unsigned char* lds, const Gemm g, const Sched& S, const Epi& E) {
;     ...
;     if constexpr (SP2) {
;         PG8_STAGE(PG8_SB(0, 0), cB, voffB); PG8_STAGE(PG8_SB(0, 1), cB + hstepB, voffB); PG8_STAGE(PG8_SA(0, 0), cA, voffA); PG8_STAGE(PG8_SA(0, 1), cA + hstepA, voffA);
;         if (wr == 1) PG8_BAR;
;         PG8_WAIT_V(2); PG8_BAR;
;         PG8_STAGE(PG8_SB(1, 0), cB + kstepB, voffB); PG8_STAGE(PG8_SA(1, 0), cA + kstepA, voffA); PG8_STAGE(PG8_SB(1, 1), cB + hstepB + kstepB, voffB);
;         PG8_WAIT_V(6); PG8_BAR;
.LBB0_179:
	s_and_b32 s7, s3, 3
	s_lshl_b32 s6, s5, 6
	s_lshl_b32 s5, s5, 13
	s_lshl_b32 s7, s7, 12
	s_add_u32 s8, s22, 0x8000
	v_mov_b32_e32 v141, v2
	s_addc_u32 s9, s23, 0
	s_add_i32 m0, s19, 0x18000
	v_lshl_add_u64 v[10:11], s[8:9], 0, v[140:141]
	v_mov_b32_e32 v137, v2
	global_load_lds_dwordx4 v[10:11], off
	s_add_i32 m0, s19, 0x1a000
	v_lshl_add_u64 v[10:11], s[8:9], 0, v[136:137]
	s_add_u32 s8, s20, 0x8000
	v_mov_b32_e32 v143, v2
	s_addc_u32 s9, s21, 0
	s_add_i32 s62, s19, 0x8000
	v_mov_b32_e32 v139, v2
	global_load_lds_dwordx4 v[10:11], off
	v_lshl_add_u64 v[10:11], s[8:9], 0, v[142:143]
	s_mov_b32 m0, s62
	s_add_i32 s63, s19, 0xa000
	global_load_lds_dwordx4 v[10:11], off
	v_lshl_add_u64 v[10:11], s[8:9], 0, v[138:139]
	s_add_u32 s8, s22, 0xc000
	s_mov_b32 m0, s63
	s_addc_u32 s9, s23, 0
	global_load_lds_dwordx4 v[10:11], off
	s_add_i32 m0, s19, 0x1c000
	v_lshl_add_u64 v[10:11], s[8:9], 0, v[140:141]
	global_load_lds_dwordx4 v[10:11], off
	v_lshl_add_u64 v[10:11], s[8:9], 0, v[136:137]
	s_add_i32 m0, s19, 0x1e000
	v_and_b32_e32 v12, 15, v3
	global_load_lds_dwordx4 v[10:11], off
	s_waitcnt vmcnt(8)
	s_barrier
	s_sext_i32_i16 s12, s2
	v_and_b32_e32 v11, 63, v3
	v_and_b32_e32 v10, 48, v3
	v_lshlrev_b32_e32 v3, 2, v12
	s_lshl_b32 s2, s3, 9
	v_lshl_or_b32 v13, v12, 6, v10
	v_and_b32_e32 v14, 32, v3
	s_add_i32 s64, s2, 0
	v_bitop3_b32 v160, v13, s7, v14 bitop3:0xde
	s_add_i32 s64, s64, 0x20000
	s_ashr_i32 s7, s6, 31
	s_cmpk_lt_u32 s4, 0x100
	v_bitop3_b32 v16, v13, s5, v14 bitop3:0xde
	s_cselect_b64 s[4:5], -1, 0
	s_bfe_u32 s82, s3, 0x10001
	v_or_b32_e32 v12, s6, v12
	v_mov_b32_e32 v13, s7
	s_lshl_b64 s[6:7], s[6:7], 2
	v_readlane_b32 s2, v252, 25
	s_add_u32 s6, s2, s6
	v_readlane_b32 s2, v252, 26
	v_lshlrev_b64 v[12:13], 7, v[12:13]
	s_addc_u32 s7, s2, s7
	s_lshl_b32 s2, s3, 6
	v_lshl_add_u64 v[12:13], s[96:97], 0, v[12:13]
	s_and_b32 s2, s2, 64
	s_mov_b32 s3, s83
	v_lshlrev_b32_e32 v14, 2, v11
	v_lshl_add_u64 v[12:13], v[12:13], 0, s[2:3]
	v_mov_b32_e32 v11, v2
	v_lshl_add_u64 v[146:147], v[12:13], 0, v[10:11]
	v_lshlrev_b32_e32 v10, 10, v8
	v_and_b32_e32 v10, 0xfffff800, v10
	v_lshl_add_u32 v7, v7, 7, v10
	v_and_b32_e32 v8, 1, v8
	v_lshl_or_b32 v7, v8, 6, v7
	v_lshl_add_u32 v148, v9, 1, v7
	v_lshlrev_b32_e32 v7, 10, v4
	v_and_b32_e32 v7, 0xfffff800, v7
	s_waitcnt vmcnt(6)
	v_lshl_add_u32 v5, v5, 7, v7
	v_and_b32_e32 v4, 1, v4
	v_mov_b32_e32 v15, v2
	v_lshl_or_b32 v4, v4, 6, v5
	v_lshl_add_u64 v[144:145], s[6:7], 0, v[14:15]
	v_mov_b32_e32 v149, v2
	v_lshl_add_u32 v150, v6, 1, v4
	v_mov_b32_e32 v151, v2
	s_mov_b32 s65, 0
	v_add_u32_e32 v161, 0, v16
	s_barrier
	s_branch .LBB0_182

; #define PG8_STAGE(bufoff, gbase, voff) do { _Pragma("unroll") for (int _i = 0; _i < 2; ++_i) \
;         __builtin_amdgcn_global_load_lds((const unsigned*)((const char*)(gbase) + (voff)[_i]), (PG8_LAS unsigned*)(lds + (bufoff) + ldsw + _i * 8192), 16, 0, 0); } while (0)
; #define PG8_WAIT_V(n) asm volatile("s_waitcnt vmcnt(" #n ")" ::: "memory")
; #define PG8_BAR __builtin_amdgcn_s_barrier()
; template <class Epi, class Sched, bool ALIGN_EPI = false, bool SP2 = false, bool ABLK = false, bool BBLK = false>
; __device__ __forceinline__ void gemm_phase(PG8_LAS unsigned char* lds, const Gemm g, const Sched& S, const Epi& E) {
;     ...
;     if constexpr (SP2) {
;         PG8_STAGE(PG8_SB(0, 0), cB, voffB); PG8_STAGE(PG8_SB(0, 1), cB + hstepB, voffB); PG8_STAGE(PG8_SA(0, 0), cA, voffA); PG8_STAGE(PG8_SA(0, 1), cA + hstepA, voffA);
;         if (wr == 1) PG8_BAR;
;         PG8_WAIT_V(2); PG8_BAR;
;         PG8_STAGE(PG8_SB(1, 0), cB + kstepB, voffB); PG8_STAGE(PG8_SA(1, 0), cA + kstepA, voffA); PG8_STAGE(PG8_SB(1, 1), cB + hstepB + kstepB, voffB);
;         PG8_WAIT_V(6); PG8_BAR;
.LBB0_425:
	v_lshrrev_b32_e32 v12, 1, v10
	v_and_b32_e32 v12, 24, v12
	s_lshl_b32 s0, s0, 5
	s_sext_i32_i8 s37, s3
	v_and_b32_e32 v11, 15, v10
	v_lshlrev_b32_e32 v13, 1, v12
	v_lshlrev_b32_e32 v10, 2, v10
	s_and_b32 s3, s0, 0x60
	s_waitcnt lgkmcnt(0)
	s_ashr_i32 s34, s31, 31
	v_lshl_or_b32 v3, s1, 6, v11
	v_lshl_or_b32 v11, v11, 6, v13
	s_lshl_b32 s1, s1, 13
	v_and_b32_e32 v10, 32, v10
	s_lshl_b32 s0, s3, 7
	v_bitop3_b32 v148, v11, s0, v10 bitop3:0xde
	s_add_u32 s0, s16, 0x8000
	v_mov_b32_e32 v139, v2
	v_bitop3_b32 v13, v11, s1, v10 bitop3:0xde
	s_addc_u32 s1, s17, 0
	s_add_i32 m0, s27, 0x18000
	v_lshl_add_u64 v[10:11], s[0:1], 0, v[138:139]
	v_mov_b32_e32 v143, v2
	global_load_lds_dwordx4 v[10:11], off
	s_add_i32 m0, s27, 0x1a000
	v_lshl_add_u64 v[10:11], s[0:1], 0, v[142:143]
	s_add_u32 s0, s10, 0x8000
	v_mov_b32_e32 v137, v2
	s_addc_u32 s1, s11, 0
	s_add_i32 s35, s27, 0x8000
	v_mov_b32_e32 v141, v2
	global_load_lds_dwordx4 v[10:11], off
	v_lshl_add_u64 v[10:11], s[0:1], 0, v[136:137]
	s_mov_b32 m0, s35
	s_add_i32 s70, s27, 0xa000
	global_load_lds_dwordx4 v[10:11], off
	v_lshl_add_u64 v[10:11], s[0:1], 0, v[140:141]
	s_add_u32 s0, s16, 0xc000
	s_mov_b32 m0, s70
	s_addc_u32 s1, s17, 0
	global_load_lds_dwordx4 v[10:11], off
	s_add_i32 m0, s27, 0x1c000
	v_lshl_add_u64 v[10:11], s[0:1], 0, v[138:139]
	global_load_lds_dwordx4 v[10:11], off
	v_lshl_add_u64 v[10:11], s[0:1], 0, v[142:143]
	s_add_i32 m0, s27, 0x1e000
	s_cmpk_lt_u32 s2, 0x100
	global_load_lds_dwordx4 v[10:11], off
	s_waitcnt vmcnt(8)
	s_barrier
	v_lshlrev_b32_e32 v10, 10, v4
	v_and_b32_e32 v10, 0xfffff800, v10
	v_lshl_add_u32 v5, v5, 7, v10
	v_and_b32_e32 v4, 1, v4
	v_lshl_or_b32 v4, v4, 6, v5
	v_lshl_add_u32 v144, v6, 1, v4
	v_lshlrev_b32_e32 v4, 10, v7
	v_and_b32_e32 v4, 0xfffff800, v4
	s_waitcnt vmcnt(6)
	v_lshl_add_u32 v4, v8, 7, v4
	v_and_b32_e32 v5, 1, v7
	v_lshl_or_b32 v4, v5, 6, v4
	s_cselect_b64 s[6:7], -1, 0
	v_or_b32_e32 v149, s3, v12
	v_mov_b32_e32 v145, v2
	v_lshl_add_u32 v146, v9, 1, v4
	v_mov_b32_e32 v147, v2
	s_mov_b32 s82, 0
	v_add_u32_e32 v150, 0, v13
	s_barrier
	s_branch .LBB0_428

; #define PG8_STAGE(bufoff, gbase, voff) do { _Pragma("unroll") for (int _i = 0; _i < 2; ++_i) \
;         __builtin_amdgcn_global_load_lds((const unsigned*)((const char*)(gbase) + (voff)[_i]), (PG8_LAS unsigned*)(lds + (bufoff) + ldsw + _i * 8192), 16, 0, 0); } while (0)
; #define PG8_WAIT_V(n) asm volatile("s_waitcnt vmcnt(" #n ")" ::: "memory")
; #define PG8_BAR __builtin_amdgcn_s_barrier()
; template <class Epi, class Sched, bool ALIGN_EPI = false, bool SP2 = false, bool ABLK = false, bool BBLK = false>
; __device__ __forceinline__ void gemm_phase(PG8_LAS unsigned char* lds, const Gemm g, const Sched& S, const Epi& E) {
;     ...
;     if constexpr (SP2) {
;         PG8_STAGE(PG8_SB(0, 0), cB, voffB); PG8_STAGE(PG8_SB(0, 1), cB + hstepB, voffB); PG8_STAGE(PG8_SA(0, 0), cA, voffA); PG8_STAGE(PG8_SA(0, 1), cA + hstepA, voffA);
;         if (wr == 1) PG8_BAR;
;         PG8_WAIT_V(2); PG8_BAR;
;         PG8_STAGE(PG8_SB(1, 0), cB + kstepB, voffB); PG8_STAGE(PG8_SA(1, 0), cA + kstepA, voffA); PG8_STAGE(PG8_SB(1, 1), cB + hstepB + kstepB, voffB);
;         PG8_WAIT_V(6); PG8_BAR;
.LBB0_910:
	s_lshl_b32 s8, s7, 6
	s_lshl_b32 s1, s7, 13
	s_lshl_b32 s7, s6, 5
	s_and_b32 s13, s7, 0x60
	s_lshl_b32 s7, s13, 7
	s_add_u32 s10, s22, 0x8000
	v_mov_b32_e32 v141, v2
	s_addc_u32 s11, s23, 0
	s_add_i32 m0, s31, 0x18000
	v_lshl_add_u64 v[12:13], s[10:11], 0, v[140:141]
	v_mov_b32_e32 v137, v2
	global_load_lds_dwordx4 v[12:13], off
	s_add_i32 m0, s31, 0x1a000
	v_lshl_add_u64 v[12:13], s[10:11], 0, v[136:137]
	s_add_u32 s10, s20, 0x8000
	v_mov_b32_e32 v143, v2
	s_addc_u32 s11, s21, 0
	s_add_i32 s37, s31, 0x8000
	v_mov_b32_e32 v139, v2
	global_load_lds_dwordx4 v[12:13], off
	v_lshl_add_u64 v[12:13], s[10:11], 0, v[142:143]
	s_mov_b32 m0, s37
	s_add_i32 s62, s31, 0xa000
	global_load_lds_dwordx4 v[12:13], off
	v_lshl_add_u64 v[12:13], s[10:11], 0, v[138:139]
	s_add_u32 s10, s22, 0xc000
	s_mov_b32 m0, s62
	s_addc_u32 s11, s23, 0
	global_load_lds_dwordx4 v[12:13], off
	s_add_i32 m0, s31, 0x1c000
	v_lshl_add_u64 v[12:13], s[10:11], 0, v[140:141]
	global_load_lds_dwordx4 v[12:13], off
	v_lshl_add_u64 v[12:13], s[10:11], 0, v[136:137]
	s_add_i32 m0, s31, 0x1e000
	v_and_b32_e32 v11, 63, v6
	global_load_lds_dwordx4 v[12:13], off
	s_waitcnt vmcnt(8)
	s_barrier
	v_and_b32_e32 v12, 15, v6
	v_lshrrev_b32_e32 v6, 1, v6
	v_and_b32_e32 v6, 24, v6
	v_lshlrev_b32_e32 v13, 1, v6
	v_lshlrev_b32_e32 v154, 2, v12
	v_or_b32_e32 v3, s8, v12
	v_lshl_or_b32 v13, v12, 6, v13
	v_and_b32_e32 v12, 32, v154
	v_or_b32_e32 v156, s13, v6
	v_lshlrev_b32_e32 v6, 10, v9
	v_bitop3_b32 v14, v13, s1, v12 bitop3:0xde
	s_lshl_b32 s1, s6, 9
	v_and_b32_e32 v6, 0xfffff800, v6
	s_add_i32 s63, s1, 0
	v_lshl_add_u32 v6, v8, 7, v6
	v_and_b32_e32 v8, 1, v9
	s_add_i32 s63, s63, 0x20000
	s_ashr_i32 s9, s8, 31
	v_lshl_or_b32 v6, v8, 6, v6
	s_cmpk_lt_u32 s3, 0x100
	v_lshl_add_u32 v146, v10, 1, v6
	v_lshlrev_b32_e32 v6, 10, v4
	s_sext_i32_i8 s12, s2
	v_bitop3_b32 v155, v13, s7, v12 bitop3:0xde
	s_cselect_b64 s[6:7], -1, 0
	s_lshl_b64 s[2:3], s[8:9], 2
	v_readlane_b32 s1, v252, 25
	v_and_b32_e32 v6, 0xfffff800, v6
	s_waitcnt vmcnt(6)
	s_add_u32 s2, s1, s2
	v_readlane_b32 s1, v252, 26
	v_lshl_add_u32 v5, v5, 7, v6
	v_and_b32_e32 v4, 1, v4
	s_addc_u32 s3, s1, s3
	v_lshlrev_b32_e32 v12, 2, v11
	v_mov_b32_e32 v13, v2
	v_lshl_or_b32 v4, v4, 6, v5
	v_lshl_add_u64 v[144:145], s[2:3], 0, v[12:13]
	v_mov_b32_e32 v147, v2
	v_lshl_add_u32 v148, v7, 1, v4
	v_mov_b32_e32 v149, v2
	s_mov_b32 s64, 0
	v_add_u32_e32 v157, 0, v14
	s_barrier
	s_branch .LBB0_913

; #define PG8_STAGE(bufoff, gbase, voff) do { _Pragma("unroll") for (int _i = 0; _i < 2; ++_i) \
;         __builtin_amdgcn_global_load_lds((const unsigned*)((const char*)(gbase) + (voff)[_i]), (PG8_LAS unsigned*)(lds + (bufoff) + ldsw + _i * 8192), 16, 0, 0); } while (0)
; #define PG8_WAIT_V(n) asm volatile("s_waitcnt vmcnt(" #n ")" ::: "memory")
; #define PG8_BAR __builtin_amdgcn_s_barrier()
; template <class Epi, class Sched, bool ALIGN_EPI = false, bool SP2 = false, bool ABLK = false, bool BBLK = false>
; __device__ __forceinline__ void gemm_phase(PG8_LAS unsigned char* lds, const Gemm g, const Sched& S, const Epi& E) {
;     ...
;     if constexpr (SP2) {
;         PG8_STAGE(PG8_SB(0, 0), cB, voffB); PG8_STAGE(PG8_SB(0, 1), cB + hstepB, voffB); PG8_STAGE(PG8_SA(0, 0), cA, voffA); PG8_STAGE(PG8_SA(0, 1), cA + hstepA, voffA);
;         if (wr == 1) PG8_BAR;
;         PG8_WAIT_V(2); PG8_BAR;
;         PG8_STAGE(PG8_SB(1, 0), cB + kstepB, voffB); PG8_STAGE(PG8_SA(1, 0), cA + kstepA, voffA); PG8_STAGE(PG8_SB(1, 1), cB + hstepB + kstepB, voffB);
;         PG8_WAIT_V(6); PG8_BAR;
.LBB0_2101:
	v_lshrrev_b32_e32 v12, 1, v10
	v_and_b32_e32 v12, 24, v12
	v_and_b32_e32 v11, 15, v10
	v_lshlrev_b32_e32 v13, 1, v12
	v_lshlrev_b32_e32 v10, 2, v10
	s_sext_i32_i8 s71, s4
	v_lshl_or_b32 v3, s7, 6, v11
	v_lshl_or_b32 v11, v11, 6, v13
	s_lshl_b32 s4, s7, 13
	v_and_b32_e32 v10, 32, v10
	v_bitop3_b32 v13, v11, s4, v10 bitop3:0xde
	s_lshl_b32 s4, s6, 5
	s_and_b32 s4, s4, 0x60
	s_waitcnt lgkmcnt(0)
	s_ashr_i32 s63, s62, 31
	s_lshl_b32 s6, s4, 7
	v_bitop3_b32 v148, v11, s6, v10 bitop3:0xde
	s_add_u32 s6, s24, 0x8000
	v_mov_b32_e32 v139, v2
	s_addc_u32 s7, s25, 0
	s_add_i32 m0, s9, 0x18000
	v_lshl_add_u64 v[10:11], s[6:7], 0, v[138:139]
	v_mov_b32_e32 v143, v2
	global_load_lds_dwordx4 v[10:11], off
	s_add_i32 m0, s9, 0x1a000
	v_lshl_add_u64 v[10:11], s[6:7], 0, v[142:143]
	s_add_u32 s6, s22, 0x8000
	v_mov_b32_e32 v137, v2
	s_addc_u32 s7, s23, 0
	s_add_i32 s64, s9, 0x8000
	v_mov_b32_e32 v141, v2
	global_load_lds_dwordx4 v[10:11], off
	v_lshl_add_u64 v[10:11], s[6:7], 0, v[136:137]
	s_mov_b32 m0, s64
	s_add_i32 s65, s9, 0xa000
	global_load_lds_dwordx4 v[10:11], off
	v_lshl_add_u64 v[10:11], s[6:7], 0, v[140:141]
	s_add_u32 s6, s24, 0xc000
	s_mov_b32 m0, s65
	s_addc_u32 s7, s25, 0
	global_load_lds_dwordx4 v[10:11], off
	s_add_i32 m0, s9, 0x1c000
	v_lshl_add_u64 v[10:11], s[6:7], 0, v[138:139]
	global_load_lds_dwordx4 v[10:11], off
	v_lshl_add_u64 v[10:11], s[6:7], 0, v[142:143]
	s_add_i32 m0, s9, 0x1e000
	s_cmpk_lt_u32 s5, 0x100
	global_load_lds_dwordx4 v[10:11], off
	s_waitcnt vmcnt(8)
	s_barrier
	v_lshlrev_b32_e32 v10, 10, v4
	v_and_b32_e32 v10, 0xfffff800, v10
	v_lshl_add_u32 v5, v5, 7, v10
	v_and_b32_e32 v4, 1, v4
	v_lshl_or_b32 v4, v4, 6, v5
	v_lshl_add_u32 v144, v6, 1, v4
	v_lshlrev_b32_e32 v4, 10, v7
	v_and_b32_e32 v4, 0xfffff800, v4
	s_waitcnt vmcnt(6)
	v_lshl_add_u32 v4, v8, 7, v4
	v_and_b32_e32 v5, 1, v7
	v_lshl_or_b32 v4, v5, 6, v4
	s_cselect_b64 s[6:7], -1, 0
	v_or_b32_e32 v149, s4, v12
	v_mov_b32_e32 v145, v2
	v_lshl_add_u32 v146, v9, 1, v4
	v_mov_b32_e32 v147, v2
	s_mov_b32 s70, 0
	v_add_u32_e32 v150, 0, v13
	s_barrier
	s_branch .LBB0_2104
